# strategy 9 (sec 7.12): attention step's wave-uniform act/actn/diagonal branch tests moved from VALU v_cmp to SALU s_cmp (on v52)
# speedup vs baseline: 1.0098x; 1.0064x over previous
.LBB0_201:
	s_or_b64 exec, exec, s[6:7]
	v_mov_b32_e32 v0, s97
	s_waitcnt lgkmcnt(0)
	s_barrier
	ds_read_b32 v0, v0
	s_movk_i32 s6, 0x17f
	s_waitcnt lgkmcnt(0)
	s_barrier
	v_cmp_lt_u32_e32 vcc, s6, v0
	v_readfirstlane_b32 s4, v0
	s_mov_b64 s[6:7], -1
	s_cbranch_vccnz .LBB0_196
	s_add_i32 s4, s4, s26
	s_and_b32 s6, s4, 0xffff
	s_mul_i32 s6, s6, 0xaaab
	s_lshr_b32 s8, s6, 20
	s_mul_i32 s6, s8, 24
	s_sub_i32 s9, s4, s6
	s_mul_i32 s4, s9, 0xab
	s_lshl_b32 s7, s8, 7
	s_bfe_u32 s4, s4, 0x6000a
	v_subrev_u32_e32 v26, s7, v199
	s_mul_i32 s6, s4, 6
	v_add_u32_e32 v212, 0xf80, v26
	s_sub_i32 s6, s9, s6
	v_readfirstlane_b32 s98, v212
	s_add_i32 s99, s98, 31
	v_or_b32_e32 v213, v212, v181
	s_lshl_b32 s7, s4, 12
	v_add_lshl_u32 v160, v213, s7, 11
	s_and_b32 s10, s6, 0xff
	v_lshl_add_u64 v[0:1], s[64:65], 0, v[160:161]
	s_lshl_b32 s4, s10, 8
	v_lshl_add_u64 v[0:1], v[0:1], 0, s[4:5]
	v_lshl_add_u64 v[0:1], v[176:177], 1, v[0:1]
	v_mov_b32_e32 v189, v161
	v_lshl_add_u64 v[24:25], v[0:1], 0, v[188:189]
	v_add_u32_e32 v2, s7, v200
	v_mov_b64_e32 v[0:1], s[30:31]
	v_mad_i64_i32 v[0:1], s[6:7], v2, s35, v[0:1]
	v_lshl_add_u64 v[0:1], v[0:1], 0, s[4:5]
	s_lshl_b32 s4, s9, 7
	v_mov_b32_e32 v191, v161
	s_and_b32 s4, s4, 0xff80
	v_lshl_add_u64 v[194:195], v[0:1], 0, v[190:191]
	v_lshl_add_u64 v[0:1], s[4:5], 0, v[178:179]
	s_mov_b32 s4, 0xc000
	v_lshlrev_b64 v[0:1], 13, v[0:1]
	v_add_co_u32_e32 v8, vcc, s4, v194
	v_lshl_add_u64 v[196:197], v[182:183], 0, v[0:1]
	s_nop 0
	v_addc_co_u32_e32 v9, vcc, 0, v195, vcc
	s_mov_b32 s4, 0x80000
	v_add_co_u32_e32 v12, vcc, s4, v196
	s_mov_b32 s4, 0x18000
	s_nop 0
	v_addc_co_u32_e32 v13, vcc, 0, v197, vcc
	global_load_dwordx4 v[0:3], v[194:195], off
	global_load_dwordx4 v[4:7], v[196:197], off
	s_nop 0
	global_load_dwordx4 v[8:11], v[8:9], off
	s_nop 0
	global_load_dwordx4 v[12:15], v[12:13], off
	v_add_co_u32_e32 v16, vcc, s4, v194
	s_mov_b32 s4, 0x24000
	s_nop 0
	v_addc_co_u32_e32 v17, vcc, 0, v195, vcc
	v_add_co_u32_e32 v20, vcc, s4, v194
	s_mov_b32 s24, 1
	s_nop 0
	v_addc_co_u32_e32 v21, vcc, 0, v195, vcc
	global_load_dwordx4 v[16:19], v[16:17], off
	s_nop 0
	global_load_dwordx4 v[20:23], v[20:21], off
	s_nop 0
	global_load_dwordx4 v[128:131], v[24:25], off
	global_load_dwordx4 v[132:135], v[24:25], off offset:32
	global_load_dwordx4 v[136:139], v[24:25], off offset:64
	global_load_dwordx4 v[140:143], v[24:25], off offset:96
	v_add_u32_e32 v189, 0xc800, v211
	v_add_u32_e32 v191, 0xf000, v211
	s_lshl_b32 s27, s10, 7
	s_lshl_b32 s22, s8, 1
	s_waitcnt vmcnt(9)
	ds_write_b128 v175, v[0:3]
	s_waitcnt vmcnt(7)
	ds_write_b128 v175, v[8:11] offset:8704
	ds_write2_b64 v189, v[4:5], v[6:7] offset0:128 offset1:130
	s_waitcnt vmcnt(6)
	ds_write2_b64 v191, v[12:13], v[14:15] offset1:2
	s_waitcnt vmcnt(5)
	ds_write_b128 v175, v[16:19] offset:17408
	s_waitcnt vmcnt(4)
	ds_write_b128 v175, v[20:23] offset:26112
	s_waitcnt lgkmcnt(0)
	s_barrier
	s_setprio 1
	v_add_u32_e32 v8, v203, v204
	ds_read_b128 v[0:3], v8
	ds_read_b128 v[4:7], v8 offset:32
	s_mov_b32 s4, s5
	s_mov_b32 s6, s5
	s_mov_b32 s7, s5
	s_waitcnt vmcnt(3) lgkmcnt(1)
	v_mfma_f32_32x32x16_bf16 v[64:79], v[0:3], v[128:131], 0
	s_mov_b32 s8, s5
	s_mov_b32 s9, s5
	s_mov_b32 s10, s5
	s_mov_b32 s11, s5
	s_mov_b32 s12, s5
	s_mov_b32 s13, s5
	s_mov_b32 s14, s5
	s_waitcnt vmcnt(2) lgkmcnt(0)
	v_mfma_f32_32x32x16_bf16 v[64:79], v[4:7], v[132:135], v[64:79]
	ds_read_b128 v[0:3], v8 offset:64
	ds_read_b128 v[4:7], v8 offset:96
	s_mov_b32 s15, s5
	s_mov_b32 s16, s5
	s_mov_b32 s17, s5
	s_mov_b32 s18, s5
	s_mov_b32 s19, s5
	s_waitcnt vmcnt(1) lgkmcnt(1)
	v_mfma_f32_32x32x16_bf16 v[64:79], v[0:3], v[136:139], v[64:79]
	s_waitcnt vmcnt(0) lgkmcnt(0)
	v_mfma_f32_32x32x16_bf16 v[64:79], v[4:7], v[140:143], v[64:79]
	ds_read_b128 v[0:3], v8 offset:8704
	ds_read_b128 v[4:7], v8 offset:8736
	ds_read_b128 v[16:19], v8 offset:8800
	s_waitcnt lgkmcnt(2)
	v_mfma_f32_32x32x16_bf16 v[80:95], v[0:3], v[128:131], 0
	ds_read_b128 v[0:3], v8 offset:8768
	s_waitcnt lgkmcnt(2)
	v_mfma_f32_32x32x16_bf16 v[80:95], v[4:7], v[132:135], v[80:95]
	s_waitcnt lgkmcnt(0)
	v_mfma_f32_32x32x16_bf16 v[80:95], v[0:3], v[136:139], v[80:95]
	v_mov_b64_e32 v[0:1], s[4:5]
	v_mov_b64_e32 v[2:3], s[6:7]
	v_mov_b64_e32 v[4:5], s[8:9]
	v_mov_b64_e32 v[6:7], s[10:11]
	v_mov_b64_e32 v[8:9], s[12:13]
	v_mov_b64_e32 v[10:11], s[14:15]
	v_mov_b64_e32 v[12:13], s[16:17]
	v_mfma_f32_32x32x16_bf16 v[80:95], v[16:19], v[140:143], v[80:95]
	v_mov_b64_e32 v[14:15], s[18:19]
	s_sub_i32 s12, 64, s22
	s_setprio 0
	v_add_u32_e32 v214, 0xf9f, v26
	v_mov_b64_e32 v[30:31], v[14:15]
	v_mov_b64_e32 v[46:47], v[14:15]
	v_mov_b64_e32 v[62:63], v[14:15]
	s_mov_b32 s13, 63
	s_sub_i32 s14, 63, s22
	s_mov_b32 s16, 2
	v_mov_b32_e32 v170, 0xff800000
	v_mov_b32_e32 v215, 0
	s_mov_b32 s15, 3
	v_mov_b64_e32 v[28:29], v[12:13]
	v_mov_b64_e32 v[26:27], v[10:11]
	v_mov_b64_e32 v[24:25], v[8:9]
	v_mov_b64_e32 v[22:23], v[6:7]
	v_mov_b64_e32 v[20:21], v[4:5]
	v_mov_b64_e32 v[18:19], v[2:3]
	v_mov_b64_e32 v[16:17], v[0:1]
	v_mov_b64_e32 v[44:45], v[12:13]
	v_mov_b64_e32 v[42:43], v[10:11]
	v_mov_b64_e32 v[40:41], v[8:9]
	v_mov_b64_e32 v[38:39], v[6:7]
	v_mov_b64_e32 v[36:37], v[4:5]
	v_mov_b64_e32 v[34:35], v[2:3]
	v_mov_b64_e32 v[32:33], v[0:1]
	v_mov_b64_e32 v[60:61], v[12:13]
	v_mov_b64_e32 v[58:59], v[10:11]
	v_mov_b64_e32 v[56:57], v[8:9]
	v_mov_b64_e32 v[54:55], v[6:7]
	v_mov_b64_e32 v[52:53], v[4:5]
	v_mov_b64_e32 v[50:51], v[2:3]
	v_mov_b64_e32 v[48:49], v[0:1]
	s_branch .LBB0_205

.LBB0_205:
	s_add_i32 s17, s15, -1
	s_cmp_lt_u32 s17, s12
	s_cselect_b64 s[6:7], -1, 0
	s_and_b64 s[8:9], s[6:7], exec
	s_cselect_b32 s4, s17, s14
	s_lshl_b32 s4, s4, 6
	s_add_i32 s18, s15, -2
	s_or_b32 s19, s4, 32
	s_cmp_lt_u32 s18, s12
	s_cselect_b64 s[8:9], -1, 0
	v_mad_u64_u32 v[144:145], s[10:11], s4, v228, v[194:195]
	v_mad_u64_u32 v[148:149], s[10:11], s19, v228, v[194:195]
	s_and_b64 s[10:11], s[8:9], exec
	s_cselect_b32 s10, s18, s14
	s_lshl_b32 s10, s10, 6
	s_mov_b32 s11, s5
	v_lshl_add_u64 v[152:153], s[10:11], 1, v[196:197]
	v_add_co_u32_e32 v154, vcc, 0x80000, v152
	global_load_dwordx4 v[144:147], v[144:145], off
	s_nop 0
	global_load_dwordx4 v[148:151], v[148:149], off
	v_addc_co_u32_e32 v155, vcc, 0, v153, vcc
	global_load_dwordx4 v[156:159], v[152:153], off
	s_nop 0
	global_load_dwordx4 v[152:155], v[154:155], off
	s_sub_i32 s10, s13, 30
	s_cmp_le_u32 s10, s98
	s_cselect_b64 s[10:11], s[8:9], 0
	s_and_saveexec_b64 s[8:9], s[10:11]
	s_cbranch_execz .LBB0_207
	s_mul_i32 s10, s24, 0x4400
	s_setprio 1
	v_add3_u32 v162, v203, s10, v204
	ds_read_b128 v[112:115], v162
	ds_read_b128 v[116:119], v162 offset:32
	ds_read_b128 v[120:123], v162 offset:64
	ds_read_b128 v[124:127], v162 offset:96
	ds_read_b128 v[222:225], v162 offset:8704
	ds_read_b128 v[236:239], v162 offset:8736
	ds_read_b128 v[240:243], v162 offset:8768
	ds_read_b128 v[244:247], v162 offset:8800
	s_waitcnt lgkmcnt(7)
	v_mfma_f32_32x32x16_bf16 v[96:111], v[112:115], v[128:131], 0
	s_waitcnt lgkmcnt(6)
	v_mfma_f32_32x32x16_bf16 v[96:111], v[116:119], v[132:135], v[96:111]
	s_waitcnt lgkmcnt(5)
	v_mfma_f32_32x32x16_bf16 v[96:111], v[120:123], v[136:139], v[96:111]
	s_waitcnt lgkmcnt(4)
	v_mfma_f32_32x32x16_bf16 v[96:111], v[124:127], v[140:143], v[96:111]
	s_waitcnt lgkmcnt(3)
	v_mfma_f32_32x32x16_bf16 v[112:127], v[222:225], v[128:131], 0
	s_waitcnt lgkmcnt(2)
	v_mfma_f32_32x32x16_bf16 v[112:127], v[236:239], v[132:135], v[112:127]
	s_waitcnt lgkmcnt(1)
	v_mfma_f32_32x32x16_bf16 v[112:127], v[240:243], v[136:139], v[112:127]
	s_waitcnt lgkmcnt(0)
	v_mfma_f32_32x32x16_bf16 v[112:127], v[244:247], v[140:143], v[112:127]
	s_setprio 0
.LBB0_207:
	s_or_b64 exec, exec, s[8:9]
	s_sub_i32 s8, s13, 63
	s_cmp_le_u32 s8, s99
	s_cselect_b64 vcc, exec, 0
	s_and_saveexec_b64 s[8:9], vcc
	s_cbranch_execz .LBB0_213
	s_cmp_gt_u32 s13, s98
	s_cselect_b64 vcc, exec, 0
	s_and_saveexec_b64 s[10:11], vcc
	s_cbranch_execz .LBB0_210
	v_add_u32_e32 v162, s13, v180
	v_subrev_u32_e32 v163, 63, v162
	v_cmp_le_u32_e32 vcc, v163, v213
	s_nop 1
	v_cndmask_b32_e32 v64, v229, v64, vcc
	v_cmp_lt_u32_e32 vcc, v163, v213
	v_subrev_u32_e32 v163, 61, v162
	s_nop 0
	v_cndmask_b32_e32 v65, v229, v65, vcc
	v_cmp_le_u32_e32 vcc, v163, v213
	v_subrev_u32_e32 v163, 60, v162
	s_nop 0
	v_cndmask_b32_e32 v66, v229, v66, vcc
	v_cmp_le_u32_e32 vcc, v163, v213
	v_subrev_u32_e32 v163, 55, v162
	s_nop 0
	v_cndmask_b32_e32 v67, v229, v67, vcc
	v_cmp_le_u32_e32 vcc, v163, v213
	v_subrev_u32_e32 v163, 54, v162
	s_nop 0
	v_cndmask_b32_e32 v68, v229, v68, vcc
	v_cmp_le_u32_e32 vcc, v163, v213
	v_subrev_u32_e32 v163, 53, v162
	s_nop 0
	v_cndmask_b32_e32 v69, v229, v69, vcc
	v_cmp_le_u32_e32 vcc, v163, v213
	v_subrev_u32_e32 v163, 52, v162
	s_nop 0
	v_cndmask_b32_e32 v70, v229, v70, vcc
	v_cmp_le_u32_e32 vcc, v163, v213
	v_subrev_u32_e32 v163, 47, v162
	s_nop 0
	v_cndmask_b32_e32 v71, v229, v71, vcc
	v_cmp_le_u32_e32 vcc, v163, v213
	v_subrev_u32_e32 v163, 46, v162
	s_nop 0
	v_cndmask_b32_e32 v72, v229, v72, vcc
	v_cmp_le_u32_e32 vcc, v163, v213
	v_subrev_u32_e32 v163, 45, v162
	s_nop 0
	v_cndmask_b32_e32 v73, v229, v73, vcc
	v_cmp_le_u32_e32 vcc, v163, v213
	v_subrev_u32_e32 v163, 44, v162
	s_nop 0
	v_cndmask_b32_e32 v74, v229, v74, vcc
	v_cmp_le_u32_e32 vcc, v163, v213
	v_subrev_u32_e32 v163, 39, v162
	s_nop 0
	v_cndmask_b32_e32 v75, v229, v75, vcc
	v_cmp_le_u32_e32 vcc, v163, v213
	v_subrev_u32_e32 v163, 38, v162
	s_nop 0
	v_cndmask_b32_e32 v76, v229, v76, vcc
	v_cmp_le_u32_e32 vcc, v163, v213
	v_subrev_u32_e32 v163, 37, v162
	s_nop 0
	v_cndmask_b32_e32 v77, v229, v77, vcc
	v_cmp_le_u32_e32 vcc, v163, v213
	v_subrev_u32_e32 v163, 36, v162
	s_nop 0
	v_cndmask_b32_e32 v78, v229, v78, vcc
	v_cmp_le_u32_e32 vcc, v163, v213
	v_subrev_u32_e32 v163, 31, v162
	s_nop 0
	v_cndmask_b32_e32 v79, v229, v79, vcc
	v_cmp_le_u32_e32 vcc, v163, v213
	v_subrev_u32_e32 v163, 30, v162
	s_nop 0
	v_cndmask_b32_e32 v80, v229, v80, vcc
	v_cmp_le_u32_e32 vcc, v163, v213
	v_subrev_u32_e32 v163, 29, v162
	s_nop 0
	v_cndmask_b32_e32 v81, v229, v81, vcc
	v_cmp_le_u32_e32 vcc, v163, v213
	v_subrev_u32_e32 v163, 28, v162
	s_nop 0
	v_cndmask_b32_e32 v82, v229, v82, vcc
	v_cmp_le_u32_e32 vcc, v163, v213
	v_subrev_u32_e32 v163, 23, v162
	s_nop 0
	v_cndmask_b32_e32 v83, v229, v83, vcc
	v_cmp_le_u32_e32 vcc, v163, v213
	v_subrev_u32_e32 v163, 22, v162
	s_nop 0
	v_cndmask_b32_e32 v84, v229, v84, vcc
	v_cmp_le_u32_e32 vcc, v163, v213
	v_subrev_u32_e32 v163, 21, v162
	s_nop 0
	v_cndmask_b32_e32 v85, v229, v85, vcc
	v_cmp_le_u32_e32 vcc, v163, v213
	v_subrev_u32_e32 v163, 20, v162
	s_nop 0
	v_cndmask_b32_e32 v86, v229, v86, vcc
	v_cmp_le_u32_e32 vcc, v163, v213
	v_add_u32_e32 v163, -15, v162
	s_nop 0
	v_cndmask_b32_e32 v87, v229, v87, vcc
	v_cmp_le_u32_e32 vcc, v163, v213
	v_add_u32_e32 v163, -14, v162
	s_nop 0
	v_cndmask_b32_e32 v88, v229, v88, vcc
	v_cmp_le_u32_e32 vcc, v163, v213
	v_add_u32_e32 v163, -13, v162
	s_nop 0
	v_cndmask_b32_e32 v89, v229, v89, vcc
	v_cmp_le_u32_e32 vcc, v163, v213
	v_add_u32_e32 v163, -12, v162
	s_nop 0
	v_cndmask_b32_e32 v90, v229, v90, vcc
	v_cmp_le_u32_e32 vcc, v163, v213
	v_add_u32_e32 v163, -7, v162
	s_nop 0
	v_cndmask_b32_e32 v91, v229, v91, vcc
	v_cmp_le_u32_e32 vcc, v163, v213
	v_add_u32_e32 v163, -6, v162
	s_nop 0
	v_cndmask_b32_e32 v92, v229, v92, vcc
	v_cmp_le_u32_e32 vcc, v163, v213
	v_add_u32_e32 v163, -5, v162
	v_add_u32_e32 v162, -4, v162
	v_cndmask_b32_e32 v93, v229, v93, vcc
	v_cmp_le_u32_e32 vcc, v163, v213
	s_nop 1
	v_cndmask_b32_e32 v94, v229, v94, vcc
	v_cmp_le_u32_e32 vcc, v162, v213
	s_nop 1
	v_cndmask_b32_e32 v95, v229, v95, vcc

.LBB0_213:
	s_or_b64 exec, exec, s[8:9]
	s_mul_i32 s8, s16, 0x4400
	v_add_u32_e32 v162, s8, v175
	s_cmp_lt_u32 s15, s12
	s_waitcnt vmcnt(3)
	ds_write_b128 v162, v[144:147]
	s_waitcnt vmcnt(2)
	ds_write_b128 v162, v[148:151] offset:8704
	s_waitcnt vmcnt(1)
	ds_write2_b64 v208, v[156:157], v[158:159] offset1:2
	v_add_u32_e32 v144, 0x2000, v208
	s_cselect_b32 s9, s15, s14
	s_waitcnt vmcnt(0)
	ds_write2_b64 v144, v[152:153], v[154:155] offset0:128 offset1:130
	s_lshl_b32 s9, s9, 6
	v_lshl_add_u64 v[152:153], s[4:5], 1, v[196:197]
	v_mad_u64_u32 v[144:145], s[10:11], s9, v228, v[194:195]
	s_or_b32 s9, s9, 32
	v_add_co_u32_e32 v154, vcc, 0x80000, v152
	v_mad_u64_u32 v[148:149], s[10:11], s9, v228, v[194:195]
	s_nop 0
	v_addc_co_u32_e32 v155, vcc, 0, v153, vcc
	s_waitcnt lgkmcnt(0)
	s_barrier
	global_load_dwordx4 v[144:147], v[144:145], off
	s_nop 0
	global_load_dwordx4 v[148:151], v[148:149], off
	s_nop 0
	global_load_dwordx4 v[156:159], v[152:153], off
	s_nop 0
	global_load_dwordx4 v[152:155], v[154:155], off
	s_add_i32 s4, s13, 34
	s_cmp_le_u32 s4, s98
	s_cselect_b64 s[10:11], s[6:7], 0
	s_and_saveexec_b64 s[6:7], s[10:11]
	s_cbranch_execz .LBB0_215
	s_setprio 1
	v_add3_u32 v162, v203, s8, v204
	ds_read_b128 v[80:83], v162
	ds_read_b128 v[84:87], v162 offset:32
	ds_read_b128 v[88:91], v162 offset:64
	ds_read_b128 v[92:95], v162 offset:96
	ds_read_b128 v[222:225], v162 offset:8704
	ds_read_b128 v[236:239], v162 offset:8736
	ds_read_b128 v[240:243], v162 offset:8768
	ds_read_b128 v[244:247], v162 offset:8800
	s_waitcnt lgkmcnt(7)
	v_mfma_f32_32x32x16_bf16 v[64:79], v[80:83], v[128:131], 0
	s_waitcnt lgkmcnt(6)
	v_mfma_f32_32x32x16_bf16 v[64:79], v[84:87], v[132:135], v[64:79]
	s_waitcnt lgkmcnt(5)
	v_mfma_f32_32x32x16_bf16 v[64:79], v[88:91], v[136:139], v[64:79]
	s_waitcnt lgkmcnt(4)
	v_mfma_f32_32x32x16_bf16 v[64:79], v[92:95], v[140:143], v[64:79]
	s_waitcnt lgkmcnt(3)
	v_mfma_f32_32x32x16_bf16 v[80:95], v[222:225], v[128:131], 0
	s_waitcnt lgkmcnt(2)
	v_mfma_f32_32x32x16_bf16 v[80:95], v[236:239], v[132:135], v[80:95]
	s_waitcnt lgkmcnt(1)
	v_mfma_f32_32x32x16_bf16 v[80:95], v[240:243], v[136:139], v[80:95]
	s_waitcnt lgkmcnt(0)
	v_mfma_f32_32x32x16_bf16 v[80:95], v[244:247], v[140:143], v[80:95]
	s_setprio 0
.LBB0_215:
	s_or_b64 exec, exec, s[6:7]
	s_add_i32 s4, s13, 1
	s_cmp_le_u32 s4, s99
	s_cselect_b64 vcc, exec, 0
	s_and_saveexec_b64 s[6:7], vcc
	s_cbranch_execz .LBB0_204
	s_add_i32 s4, s13, 64
	s_cmp_gt_u32 s4, s98
	s_cselect_b64 vcc, exec, 0
	s_and_saveexec_b64 s[8:9], vcc
	s_cbranch_execz .LBB0_218
	v_add_u32_e32 v162, s13, v180
	v_add_u32_e32 v163, 1, v162
	v_cmp_lt_u32_e32 vcc, v163, v213
	s_nop 1
	v_cndmask_b32_e32 v97, v229, v97, vcc
	v_cmp_le_u32_e32 vcc, v163, v213
	v_add_u32_e32 v163, 3, v162
	s_nop 0
	v_cndmask_b32_e32 v96, v229, v96, vcc
	v_cmp_le_u32_e32 vcc, v163, v213
	v_add_u32_e32 v163, 4, v162
	s_nop 0
	v_cndmask_b32_e32 v98, v229, v98, vcc
	v_cmp_le_u32_e32 vcc, v163, v213
	v_add_u32_e32 v163, 9, v162
	s_nop 0
	v_cndmask_b32_e32 v99, v229, v99, vcc
	v_cmp_le_u32_e32 vcc, v163, v213
	v_add_u32_e32 v163, 10, v162
	s_nop 0
	v_cndmask_b32_e32 v100, v229, v100, vcc
	v_cmp_le_u32_e32 vcc, v163, v213
	v_add_u32_e32 v163, 11, v162
	s_nop 0
	v_cndmask_b32_e32 v101, v229, v101, vcc
	v_cmp_le_u32_e32 vcc, v163, v213
	v_add_u32_e32 v163, 12, v162
	s_nop 0
	v_cndmask_b32_e32 v102, v229, v102, vcc
	v_cmp_le_u32_e32 vcc, v163, v213
	v_add_u32_e32 v163, 17, v162
	s_nop 0
	v_cndmask_b32_e32 v103, v229, v103, vcc
	v_cmp_le_u32_e32 vcc, v163, v213
	v_add_u32_e32 v163, 18, v162
	s_nop 0
	v_cndmask_b32_e32 v104, v229, v104, vcc
	v_cmp_le_u32_e32 vcc, v163, v213
	v_add_u32_e32 v163, 19, v162
	s_nop 0
	v_cndmask_b32_e32 v105, v229, v105, vcc
	v_cmp_le_u32_e32 vcc, v163, v213
	v_add_u32_e32 v163, 20, v162
	s_nop 0
	v_cndmask_b32_e32 v106, v229, v106, vcc
	v_cmp_le_u32_e32 vcc, v163, v213
	v_add_u32_e32 v163, 25, v162
	s_nop 0
	v_cndmask_b32_e32 v107, v229, v107, vcc
	v_cmp_le_u32_e32 vcc, v163, v213
	v_add_u32_e32 v163, 26, v162
	s_nop 0
	v_cndmask_b32_e32 v108, v229, v108, vcc
	v_cmp_le_u32_e32 vcc, v163, v213
	v_add_u32_e32 v163, 27, v162
	s_nop 0
	v_cndmask_b32_e32 v109, v229, v109, vcc
	v_cmp_le_u32_e32 vcc, v163, v213
	v_add_u32_e32 v163, 28, v162
	s_nop 0
	v_cndmask_b32_e32 v110, v229, v110, vcc
	v_cmp_le_u32_e32 vcc, v163, v213
	v_add_u32_e32 v163, 33, v162
	s_nop 0
	v_cndmask_b32_e32 v111, v229, v111, vcc
	v_cmp_le_u32_e32 vcc, v163, v213
	v_add_u32_e32 v163, 34, v162
	s_nop 0
	v_cndmask_b32_e32 v112, v229, v112, vcc
	v_cmp_le_u32_e32 vcc, v163, v213
	v_add_u32_e32 v163, 35, v162
	s_nop 0
	v_cndmask_b32_e32 v113, v229, v113, vcc
	v_cmp_le_u32_e32 vcc, v163, v213
	v_add_u32_e32 v163, 36, v162
	s_nop 0
	v_cndmask_b32_e32 v114, v229, v114, vcc
	v_cmp_le_u32_e32 vcc, v163, v213
	v_add_u32_e32 v163, 41, v162
	s_nop 0
	v_cndmask_b32_e32 v115, v229, v115, vcc
	v_cmp_le_u32_e32 vcc, v163, v213
	v_add_u32_e32 v163, 42, v162
	s_nop 0
	v_cndmask_b32_e32 v116, v229, v116, vcc
	v_cmp_le_u32_e32 vcc, v163, v213
	v_add_u32_e32 v163, 43, v162
	s_nop 0
	v_cndmask_b32_e32 v117, v229, v117, vcc
	v_cmp_le_u32_e32 vcc, v163, v213
	v_add_u32_e32 v163, 44, v162
	s_nop 0
	v_cndmask_b32_e32 v118, v229, v118, vcc
	v_cmp_le_u32_e32 vcc, v163, v213
	v_add_u32_e32 v163, 49, v162
	s_nop 0
	v_cndmask_b32_e32 v119, v229, v119, vcc
	v_cmp_le_u32_e32 vcc, v163, v213
	v_add_u32_e32 v163, 50, v162
	s_nop 0
	v_cndmask_b32_e32 v120, v229, v120, vcc
	v_cmp_le_u32_e32 vcc, v163, v213
	v_add_u32_e32 v163, 51, v162
	s_nop 0
	v_cndmask_b32_e32 v121, v229, v121, vcc
	v_cmp_le_u32_e32 vcc, v163, v213
	v_add_u32_e32 v163, 52, v162
	s_nop 0
	v_cndmask_b32_e32 v122, v229, v122, vcc
	v_cmp_le_u32_e32 vcc, v163, v213
	v_add_u32_e32 v163, 57, v162
	s_nop 0
	v_cndmask_b32_e32 v123, v229, v123, vcc
	v_cmp_le_u32_e32 vcc, v163, v213
	v_add_u32_e32 v163, 58, v162
	s_nop 0
	v_cndmask_b32_e32 v124, v229, v124, vcc
	v_cmp_le_u32_e32 vcc, v163, v213
	v_add_u32_e32 v163, 59, v162
	v_add_u32_e32 v162, 60, v162
	v_cndmask_b32_e32 v125, v229, v125, vcc
	v_cmp_le_u32_e32 vcc, v163, v213
	s_nop 1
	v_cndmask_b32_e32 v126, v229, v126, vcc
	v_cmp_le_u32_e32 vcc, v162, v213
	s_nop 1
	v_cndmask_b32_e32 v127, v229, v127, vcc
